# v107 = v102 + P4 first-segment B-fragment LDS reads hoisted to the unit header
# baseline (speedup 1.0000x reference)
; #define PG8_STAGE(bufoff, gbase, voff) do { _Pragma("unroll") for (int _i = 0; _i < 2; ++_i) \
;         __builtin_amdgcn_global_load_lds((const unsigned*)((const char*)(gbase) + (voff)[_i]), (PG8_LAS unsigned*)(lds + (bufoff) + ldsw + _i * 8192), 16, 0, 0); } while (0)
; #define PG8_LDA(dst, b, h) do { _Pragma("unroll") for (int m = 0; m < 4; ++m) _Pragma("unroll") for (int k = 0; k < 2; ++k) dst[m][k] = *(const PG8_LAS bf16x8*)(lds + PG8_SA(b, h) + aoff + m * 2048 + k * 1024); } while (0)
; #define PG8_LDB(dst, b, h) do { _Pragma("unroll") for (int n = 0; n < 2; ++n) _Pragma("unroll") for (int k = 0; k < 2; ++k) dst[n][k] = *(const PG8_LAS bf16x8*)(lds + PG8_SB(b, h) + boff + n * 2048 + k * 1024); } while (0)
;     __host__ __device__ bool next(int i, Unit& u) const {
;         const long L = (long)i * G + c; if (L >= nwg) return false;
;         int wgid = (int)L; { const int q = nwg / NXCD, r = nwg % NXCD, xcd = wgid % NXCD, off = wgid / NXCD; wgid = (xcd < r ? xcd * (q + 1) : r * (q + 1) + (xcd - r) * q) + off; }
;         const int nig = WGM * nN, gid = wgid / nig, fm = gid * WGM, gsz = (nM - fm) < WGM ? (nM - fm) : WGM;
;         u.pm = fm + ((wgid % nig) % gsz); u.pn = (wgid % nig) / gsz + ((gid & 1) ? rot : 0); if (u.pn >= nN) u.pn -= nN; return true;
; template <class Epi, class Sched, bool ALIGN_EPI = false, bool SP2 = false>
; __device__ __forceinline__ void gemm_phase(PG8_LAS unsigned char* lds, const Gemm g, const Sched& S, const Epi& E) {
;     ...
;         const bool has_next = S.next(ui + 1, nxt);
;         const char* nA = has_next ? (const char*)g.A + (size_t)nxt.pm * tstep : cA; const char* nB = has_next ? (const char*)g.Bt + (size_t)nxt.pn * tstep : cB;
;         for (int t = 0; t < nt; t += 2) {
;             if constexpr (Epi::HAS_MID) { if (t == nt / 2) E.mid(acc, cur, wr, wc, fr, fq); }
;             const bool last = (t == nt - 2);
;             const char* a1 = cA + (size_t)(t + 1) * kstep;
;             const char* a2 = last ? nA : cA + (size_t)(t + 2) * kstep; const char* b2 = last ? nB : cB + (size_t)(t + 2) * kstep;
;             const char* a3 = a2 + kstep; const char* b3 = b2 + kstep;
;             if (last && has_next) S.a_ready(nxt);
;             if constexpr (SP2) {
;             PG8_LDB(B0, 0, 0); PG8_LDB(B1, 0, 1); PG8_SCHED; PG8_LDA(At, 0, 0); PG8_STAGE(PG8_SA(1, 1), a1 + hstep, voffA);
.LBB0_710:
	ds_read_b128 v[176:179], v139
	ds_read_b128 v[180:183], v139 offset:1024
	ds_read_b128 v[184:187], v139 offset:2048
	ds_read_b128 v[188:191], v139 offset:3072
	ds_read_b128 v[192:195], v139 offset:4096
	ds_read_b128 v[196:199], v139 offset:5120
	ds_read_b128 v[200:203], v139 offset:6144
	ds_read_b128 v[204:207], v139 offset:7168
	s_add_i32 s76, s29, 1
	s_and_b64 vcc, exec, s[0:1]
	s_mov_b64 s[40:41], -1
	s_cbranch_vccnz .LBB0_717
	s_mul_i32 s2, s76, s70
	s_mul_hi_u32 s31, s76, s3
	s_add_i32 s31, s31, s2
	s_mul_i32 s2, s76, s3
	s_add_u32 s42, s2, s98
	s_addc_u32 s43, s31, s71
	v_cmp_gt_i64_e32 vcc, s[42:43], v[136:137]
	s_mov_b64 s[40:41], 0
	s_mov_b64 s[44:45], 0
	s_mov_b32 s31, s36
	s_mov_b32 s37, s38
	s_cbranch_vccnz .LBB0_717
	s_ashr_i32 s2, s42, 31
	s_lshr_b32 s2, s2, 29
	s_add_i32 s31, s42, s2
	s_and_b32 s2, s31, -8
	s_sub_i32 s37, s42, s2
	s_cmp_gt_i32 s37, -1
	s_mov_b64 s[42:43], -1
	s_cbranch_scc0 .LBB0_714
	s_lshl_b32 s39, s37, 6
	s_mov_b64 s[42:43], 0

; #define PG8_STAGE(bufoff, gbase, voff) do { _Pragma("unroll") for (int _i = 0; _i < 2; ++_i) \
;         __builtin_amdgcn_global_load_lds((const unsigned*)((const char*)(gbase) + (voff)[_i]), (PG8_LAS unsigned*)(lds + (bufoff) + ldsw + _i * 8192), 16, 0, 0); } while (0)
; #define PG8_LDA(dst, b, h) do { _Pragma("unroll") for (int m = 0; m < 4; ++m) _Pragma("unroll") for (int k = 0; k < 2; ++k) dst[m][k] = *(const PG8_LAS bf16x8*)(lds + PG8_SA(b, h) + aoff + m * 2048 + k * 1024); } while (0)
; #define PG8_LDB(dst, b, h) do { _Pragma("unroll") for (int n = 0; n < 2; ++n) _Pragma("unroll") for (int k = 0; k < 2; ++k) dst[n][k] = *(const PG8_LAS bf16x8*)(lds + PG8_SB(b, h) + boff + n * 2048 + k * 1024); } while (0)
; #define PG8_MMA(ai, bj, At, Bt) do { __builtin_amdgcn_s_setprio(1); _Pragma("unroll") for (int m = 0; m < 4; ++m) _Pragma("unroll") for (int n = 0; n < 2; ++n) _Pragma("unroll") for (int k = 0; k < 2; ++k) \
;         acc[ai][bj][m][n] = __builtin_amdgcn_mfma_f32_16x16x32_bf16(Bt[n][k], At[m][k], acc[ai][bj][m][n], 0, 0, 0); __builtin_amdgcn_s_setprio(0); } while (0)
; template <class Epi, class Sched, bool ALIGN_EPI = false, bool SP2 = false>
; __device__ __forceinline__ void gemm_phase(PG8_LAS unsigned char* lds, const Gemm g, const Sched& S, const Epi& E) {
;     ...
;         const char* nA = has_next ? (const char*)g.A + (size_t)nxt.pm * tstep : cA; const char* nB = has_next ? (const char*)g.Bt + (size_t)nxt.pn * tstep : cB;
;         for (int t = 0; t < nt; t += 2) {
;             if constexpr (Epi::HAS_MID) { if (t == nt / 2) E.mid(acc, cur, wr, wc, fr, fq); }
;             const bool last = (t == nt - 2);
;             const char* a1 = cA + (size_t)(t + 1) * kstep;
;             const char* a2 = last ? nA : cA + (size_t)(t + 2) * kstep; const char* b2 = last ? nB : cB + (size_t)(t + 2) * kstep;
;             const char* a3 = a2 + kstep; const char* b3 = b2 + kstep;
;             if (last && has_next) S.a_ready(nxt);
;             if constexpr (SP2) {
;             PG8_LDB(B0, 0, 0); PG8_LDB(B1, 0, 1); PG8_SCHED; PG8_LDA(At, 0, 0); PG8_STAGE(PG8_SA(1, 1), a1 + hstep, voffA);
;             PG8_WAIT_V(8); PG8_WAIT_L(0); PG8_BAR; PG8_MMA(0, 0, At, B0); PG8_MMA(0, 1, At, B1); PG8_BAR; PG8_SCHED;
;             PG8_LDA(At, 0, 1); PG8_STAGE(PG8_SB(0, 0), b2, voffB); PG8_STAGE(PG8_SB(0, 1), b2 + hstep, voffB); PG8_STAGE(PG8_SA(0, 0), a2, voffA);
.LBB0_721:
	s_mov_b32 s36, s31
	s_mov_b32 s38, s37
	s_ashr_i32 s37, s31, 31
	s_lshl_b64 s[40:41], s[36:37], 19
	s_add_u32 s40, s33, s40
	s_addc_u32 s41, s54, s41
	s_and_b64 s[42:43], s[44:45], exec
	s_cselect_b32 s29, s41, s49
	s_cselect_b32 s31, s40, s48
	s_ashr_i32 s39, s38, 31
	s_lshl_b64 s[42:43], s[38:39], 19
	s_add_u32 s42, s55, s42
	s_addc_u32 s43, s56, s43
	s_and_b64 s[52:53], s[44:45], exec
	s_cselect_b32 s39, s43, s47
	s_cselect_b32 s77, s42, s46
	s_add_u32 s48, s48, 0x40080
	s_addc_u32 s49, s49, 0
	s_add_u32 s78, s46, 0x100
	s_addc_u32 s79, s47, 0
	s_mov_b32 s80, -2
	s_lshl_b64 s[86:87], s[36:37], 20
	s_add_u32 s86, s86, s16
	s_addc_u32 s87, s87, s17
	s_lshl_b32 s88, s38, 10
	s_add_u32 s86, s86, s88
	s_addc_u32 s87, s87, 0
	v_add_u32_e32 v140, s74, v138
	ds_read_b128 v[144:147], v140
	ds_read_b128 v[148:151], v140 offset:1024
	ds_read_b128 v[152:155], v140 offset:2048
	ds_read_b128 v[156:159], v140 offset:3072
	v_add_u32_e32 v140, s75, v138
	ds_read_b128 v[160:163], v140
	ds_read_b128 v[164:167], v140 offset:1024
	ds_read_b128 v[168:171], v140 offset:2048
	ds_read_b128 v[172:175], v140 offset:3072
	s_add_u32 s2, s48, 0xfffc0080
	s_addc_u32 s46, s49, -1
	s_cmp_eq_u32 s80, 12
	s_cselect_b32 s53, s29, s46
	s_cselect_b32 s52, s31, s2
	s_cselect_b32 s47, s39, s79
	s_cselect_b32 s46, s77, s78
	v_lshl_add_u64 v[140:141], s[48:49], 0, v[0:1]
	s_add_i32 m0, s64, 0xc000
	global_load_lds_dwordx4 v[140:141], off
	v_lshl_add_u64 v[140:141], s[48:49], 0, v[134:135]
	s_add_i32 m0, s64, 0xe000
	s_nop 0
	global_load_lds_dwordx4 v[140:141], off
	s_waitcnt vmcnt(12)
	s_waitcnt lgkmcnt(0)
	s_barrier
	s_setprio 1
	s_waitcnt lgkmcnt(0)
	v_mfma_f32_16x16x32_bf16 v[2:5], v[144:147], v[176:179], 0
	v_mfma_f32_16x16x32_bf16 v[6:9], v[152:155], v[176:179], 0
	v_mfma_f32_16x16x32_bf16 v[22:25], v[144:147], v[184:187], 0
	v_mfma_f32_16x16x32_bf16 v[18:21], v[152:155], v[184:187], 0
	v_mfma_f32_16x16x32_bf16 v[38:41], v[144:147], v[192:195], 0
	v_mfma_f32_16x16x32_bf16 v[34:37], v[152:155], v[192:195], 0
	v_mfma_f32_16x16x32_bf16 v[54:57], v[144:147], v[200:203], 0
	v_mfma_f32_16x16x32_bf16 v[50:53], v[152:155], v[200:203], 0
	v_mfma_f32_16x16x32_bf16 v[2:5], v[148:151], v[180:183], v[2:5]
	v_mfma_f32_16x16x32_bf16 v[6:9], v[156:159], v[180:183], v[6:9]
	v_mfma_f32_16x16x32_bf16 v[22:25], v[148:151], v[188:191], v[22:25]
	v_mfma_f32_16x16x32_bf16 v[18:21], v[156:159], v[188:191], v[18:21]
	v_mfma_f32_16x16x32_bf16 v[38:41], v[148:151], v[196:199], v[38:41]
	v_mfma_f32_16x16x32_bf16 v[34:37], v[156:159], v[196:199], v[34:37]
	v_mfma_f32_16x16x32_bf16 v[54:57], v[148:151], v[204:207], v[54:57]
	v_mfma_f32_16x16x32_bf16 v[50:53], v[156:159], v[204:207], v[50:53]
	v_mfma_f32_16x16x32_bf16 v[10:13], v[160:163], v[176:179], 0
	v_mfma_f32_16x16x32_bf16 v[14:17], v[168:171], v[176:179], 0
	v_mfma_f32_16x16x32_bf16 v[26:29], v[160:163], v[184:187], 0
	v_mfma_f32_16x16x32_bf16 v[30:33], v[168:171], v[184:187], 0
	v_mfma_f32_16x16x32_bf16 v[42:45], v[160:163], v[192:195], 0
	v_mfma_f32_16x16x32_bf16 v[46:49], v[168:171], v[192:195], 0
	v_mfma_f32_16x16x32_bf16 v[58:61], v[160:163], v[200:203], 0
	v_mfma_f32_16x16x32_bf16 v[62:65], v[168:171], v[200:203], 0
	v_mfma_f32_16x16x32_bf16 v[10:13], v[164:167], v[180:183], v[10:13]
	v_mfma_f32_16x16x32_bf16 v[14:17], v[172:175], v[180:183], v[14:17]
	v_mfma_f32_16x16x32_bf16 v[26:29], v[164:167], v[188:191], v[26:29]
	v_mfma_f32_16x16x32_bf16 v[30:33], v[172:175], v[188:191], v[30:33]
	v_mfma_f32_16x16x32_bf16 v[42:45], v[164:167], v[196:199], v[42:45]
	v_mfma_f32_16x16x32_bf16 v[46:49], v[172:175], v[196:199], v[46:49]
	v_mfma_f32_16x16x32_bf16 v[58:61], v[164:167], v[204:207], v[58:61]
	v_mfma_f32_16x16x32_bf16 v[62:65], v[172:175], v[204:207], v[62:65]
	s_setprio 0
	s_barrier
	s_add_i32 s2, s74, s57
	v_lshl_add_u64 v[140:141], s[46:47], 0, v[130:131]
	s_mov_b32 m0, s2
	ds_read_b128 v[176:179], v139 offset:16384
	ds_read_b128 v[180:183], v139 offset:17408
	ds_read_b128 v[184:187], v139 offset:18432
	ds_read_b128 v[188:191], v139 offset:19456
	ds_read_b128 v[192:195], v139 offset:20480
	ds_read_b128 v[196:199], v139 offset:21504
	ds_read_b128 v[200:203], v139 offset:22528
	ds_read_b128 v[204:207], v139 offset:23552
	global_load_lds_dwordx4 v[140:141], off
	s_add_i32 m0, s2, 0x2000
	s_add_u32 s82, s46, 0x40000
	v_lshl_add_u64 v[208:209], s[46:47], 0, v[132:133]
	s_addc_u32 s83, s47, 0
	s_add_i32 s2, s75, s57
	global_load_lds_dwordx4 v[208:209], off
	v_lshl_add_u64 v[210:211], s[82:83], 0, v[130:131]
	s_mov_b32 m0, s2
	v_lshl_add_u64 v[212:213], s[52:53], 0, v[132:133]
	global_load_lds_dwordx4 v[210:211], off
	v_lshl_add_u64 v[210:211], s[82:83], 0, v[132:133]
	s_add_i32 m0, s2, 0x2000
	s_nop 0
	global_load_lds_dwordx4 v[210:211], off
	v_lshl_add_u64 v[210:211], s[52:53], 0, v[130:131]
	s_mov_b32 m0, s64
	s_nop 0
	global_load_lds_dwordx4 v[210:211], off
	s_mov_b32 m0, s65
	s_nop 0
	global_load_lds_dwordx4 v[212:213], off
	s_waitcnt vmcnt(12)
	s_waitcnt lgkmcnt(0)
	s_barrier
; #define PG8_STAGE(bufoff, gbase, voff) do { _Pragma("unroll") for (int _i = 0; _i < 2; ++_i) \
;         __builtin_amdgcn_global_load_lds((const unsigned*)((const char*)(gbase) + (voff)[_i]), (PG8_LAS unsigned*)(lds + (bufoff) + ldsw + _i * 8192), 16, 0, 0); } while (0)
; #define PG8_LDA(dst, b, h) do { _Pragma("unroll") for (int m = 0; m < 4; ++m) _Pragma("unroll") for (int k = 0; k < 2; ++k) dst[m][k] = *(const PG8_LAS bf16x8*)(lds + PG8_SA(b, h) + aoff + m * 2048 + k * 1024); } while (0)
; #define PG8_LDB(dst, b, h) do { _Pragma("unroll") for (int n = 0; n < 2; ++n) _Pragma("unroll") for (int k = 0; k < 2; ++k) dst[n][k] = *(const PG8_LAS bf16x8*)(lds + PG8_SB(b, h) + boff + n * 2048 + k * 1024); } while (0)
; #define PG8_MMA(ai, bj, At, Bt) do { __builtin_amdgcn_s_setprio(1); _Pragma("unroll") for (int m = 0; m < 4; ++m) _Pragma("unroll") for (int n = 0; n < 2; ++n) _Pragma("unroll") for (int k = 0; k < 2; ++k) \
;         acc[ai][bj][m][n] = __builtin_amdgcn_mfma_f32_16x16x32_bf16(Bt[n][k], At[m][k], acc[ai][bj][m][n], 0, 0, 0); __builtin_amdgcn_s_setprio(0); } while (0)
; #define PG8_WAIT_V(n) asm volatile("s_waitcnt vmcnt(" #n ")" ::: "memory")
; #define PG8_WAIT_L(n) asm volatile("s_waitcnt lgkmcnt(" #n ")" ::: "memory")
; #define PG8_BAR __builtin_amdgcn_s_barrier()
; #define PG8_SCHED __builtin_amdgcn_sched_barrier(0)
; template <class Epi, class Sched, bool ALIGN_EPI = false, bool SP2 = false>
; __device__ __forceinline__ void gemm_phase(PG8_LAS unsigned char* lds, const Gemm g, const Sched& S, const Epi& E) {
;     ...
;             PG8_WAIT_V(8); PG8_WAIT_L(0); PG8_BAR; PG8_MMA(1, 0, At, B0); PG8_MMA(1, 1, At, B1); PG8_BAR; PG8_SCHED;
;             PG8_LDB(B0, 1, 0); PG8_LDB(B1, 1, 1); PG8_SCHED; PG8_LDA(At, 1, 0); PG8_STAGE(PG8_SA(0, 1), a2 + hstep, voffA);
;             PG8_WAIT_V(8); PG8_WAIT_L(0); PG8_BAR; PG8_MMA(0, 0, At, B0); PG8_MMA(0, 1, At, B1); PG8_BAR; PG8_SCHED;
	s_setprio 1
	s_waitcnt lgkmcnt(0)
	v_mfma_f32_16x16x32_bf16 v[70:73], v[144:147], v[176:179], 0
	v_mfma_f32_16x16x32_bf16 v[66:69], v[152:155], v[176:179], 0
	v_mfma_f32_16x16x32_bf16 v[86:89], v[144:147], v[184:187], 0
	v_mfma_f32_16x16x32_bf16 v[82:85], v[152:155], v[184:187], 0
	v_mfma_f32_16x16x32_bf16 v[102:105], v[144:147], v[192:195], 0
	v_mfma_f32_16x16x32_bf16 v[98:101], v[152:155], v[192:195], 0
	v_mfma_f32_16x16x32_bf16 v[118:121], v[144:147], v[200:203], 0
	v_mfma_f32_16x16x32_bf16 v[114:117], v[152:155], v[200:203], 0
	v_mfma_f32_16x16x32_bf16 v[70:73], v[148:151], v[180:183], v[70:73]
	v_mfma_f32_16x16x32_bf16 v[66:69], v[156:159], v[180:183], v[66:69]
	v_mfma_f32_16x16x32_bf16 v[86:89], v[148:151], v[188:191], v[86:89]
	v_mfma_f32_16x16x32_bf16 v[82:85], v[156:159], v[188:191], v[82:85]
	v_mfma_f32_16x16x32_bf16 v[102:105], v[148:151], v[196:199], v[102:105]
	v_mfma_f32_16x16x32_bf16 v[98:101], v[156:159], v[196:199], v[98:101]
	v_mfma_f32_16x16x32_bf16 v[118:121], v[148:151], v[204:207], v[118:121]
	v_mfma_f32_16x16x32_bf16 v[114:117], v[156:159], v[204:207], v[114:117]
	v_mfma_f32_16x16x32_bf16 v[74:77], v[160:163], v[176:179], 0
	v_mfma_f32_16x16x32_bf16 v[78:81], v[168:171], v[176:179], 0
	v_mfma_f32_16x16x32_bf16 v[90:93], v[160:163], v[184:187], 0
	v_mfma_f32_16x16x32_bf16 v[94:97], v[168:171], v[184:187], 0
	v_mfma_f32_16x16x32_bf16 v[106:109], v[160:163], v[192:195], 0
	v_mfma_f32_16x16x32_bf16 v[110:113], v[168:171], v[192:195], 0
	v_mfma_f32_16x16x32_bf16 v[122:125], v[160:163], v[200:203], 0
	v_mfma_f32_16x16x32_bf16 v[126:129], v[168:171], v[200:203], 0
	v_mfma_f32_16x16x32_bf16 v[74:77], v[164:167], v[180:183], v[74:77]
	v_mfma_f32_16x16x32_bf16 v[78:81], v[172:175], v[180:183], v[78:81]
	v_mfma_f32_16x16x32_bf16 v[90:93], v[164:167], v[188:191], v[90:93]
	v_mfma_f32_16x16x32_bf16 v[94:97], v[172:175], v[188:191], v[94:97]
	v_mfma_f32_16x16x32_bf16 v[106:109], v[164:167], v[196:199], v[106:109]
	v_mfma_f32_16x16x32_bf16 v[110:113], v[172:175], v[196:199], v[110:113]
	v_mfma_f32_16x16x32_bf16 v[122:125], v[164:167], v[204:207], v[122:125]
	v_mfma_f32_16x16x32_bf16 v[126:129], v[172:175], v[204:207], v[126:129]
	s_setprio 0
	s_barrier
	s_add_i32 s2, 0, 0x18000
	s_add_i32 s81, 0, 0x1c000
	v_add_u32_e32 v156, s2, v138
	v_add_u32_e32 v172, s81, v138
	ds_read_b128 v[144:147], v156
	ds_read_b128 v[148:151], v156 offset:1024
	ds_read_b128 v[152:155], v156 offset:2048
	ds_read_b128 v[156:159], v156 offset:3072
	ds_read_b128 v[160:163], v172
	ds_read_b128 v[164:167], v172 offset:1024
	ds_read_b128 v[168:171], v172 offset:2048
	ds_read_b128 v[172:175], v172 offset:3072
	s_add_u32 s52, s52, 0x40000
	s_addc_u32 s53, s53, 0
	s_mov_b32 m0, s66
	v_lshl_add_u64 v[214:215], s[52:53], 0, v[130:131]
	ds_read_b128 v[176:179], v139 offset:32768
	ds_read_b128 v[180:183], v139 offset:33792
	ds_read_b128 v[184:187], v139 offset:34816
	ds_read_b128 v[188:191], v139 offset:35840
	ds_read_b128 v[192:195], v139 offset:36864
	ds_read_b128 v[196:199], v139 offset:37888
	ds_read_b128 v[200:203], v139 offset:38912
	ds_read_b128 v[204:207], v139 offset:39936
	global_load_lds_dwordx4 v[214:215], off
	v_lshl_add_u64 v[214:215], s[52:53], 0, v[132:133]
	s_mov_b32 m0, s67
	s_nop 0
	global_load_lds_dwordx4 v[214:215], off
	s_waitcnt vmcnt(8)
	s_waitcnt lgkmcnt(0)
	s_barrier
; #define PG8_STAGE(bufoff, gbase, voff) do { _Pragma("unroll") for (int _i = 0; _i < 2; ++_i) \
;         __builtin_amdgcn_global_load_lds((const unsigned*)((const char*)(gbase) + (voff)[_i]), (PG8_LAS unsigned*)(lds + (bufoff) + ldsw + _i * 8192), 16, 0, 0); } while (0)
; #define PG8_LDA(dst, b, h) do { _Pragma("unroll") for (int m = 0; m < 4; ++m) _Pragma("unroll") for (int k = 0; k < 2; ++k) dst[m][k] = *(const PG8_LAS bf16x8*)(lds + PG8_SA(b, h) + aoff + m * 2048 + k * 1024); } while (0)
; #define PG8_MMA(ai, bj, At, Bt) do { __builtin_amdgcn_s_setprio(1); _Pragma("unroll") for (int m = 0; m < 4; ++m) _Pragma("unroll") for (int n = 0; n < 2; ++n) _Pragma("unroll") for (int k = 0; k < 2; ++k) \
;         acc[ai][bj][m][n] = __builtin_amdgcn_mfma_f32_16x16x32_bf16(Bt[n][k], At[m][k], acc[ai][bj][m][n], 0, 0, 0); __builtin_amdgcn_s_setprio(0); } while (0)
; #define PG8_WAIT_V(n) asm volatile("s_waitcnt vmcnt(" #n ")" ::: "memory")
; #define PG8_WAIT_L(n) asm volatile("s_waitcnt lgkmcnt(" #n ")" ::: "memory")
; #define PG8_BAR __builtin_amdgcn_s_barrier()
; #define PG8_SCHED __builtin_amdgcn_sched_barrier(0)
;     __device__ __forceinline__ void init(f32x4 (&acc)[2][2][4][2], const Unit& u, int wr, int wc, int fr, int fq) const {
;         asm volatile("" : "+v"(fr)); asm volatile("" : "+v"(fq));
; #pragma unroll
;         for (int ai = 0; ai < 2; ++ai)
; #pragma unroll
;             for (int m = 0; m < 4; ++m) { const size_t off = ((size_t)u.pm * 256 + 128 * ai + 64 * wr + 16 * m + fr) * DM + u.pn * 256 + 32 * wc + 4 * fq;
; #pragma unroll
;                 for (int bj = 0; bj < 2; ++bj)
; #pragma unroll
;                     for (int n = 0; n < 2; ++n) acc[ai][bj][m][n] = __builtin_nontemporal_load((const f32x4*)(x + off + bj * HALF + n * 16)); }
; template <class Epi, class Sched, bool ALIGN_EPI = false, bool SP2 = false>
; __device__ __forceinline__ void gemm_phase(PG8_LAS unsigned char* lds, const Gemm g, const Sched& S, const Epi& E) {
;     ...
;             PG8_WAIT_V(8); PG8_WAIT_L(0); PG8_BAR; PG8_MMA(0, 0, At, B0); PG8_MMA(0, 1, At, B1); PG8_BAR; PG8_SCHED;
;             PG8_LDA(At, 1, 1); PG8_STAGE(PG8_SB(1, 0), b3, voffB); PG8_STAGE(PG8_SB(1, 1), b3 + hstep, voffB); PG8_STAGE(PG8_SA(1, 0), a3, voffA);
;             PG8_WAIT_V(8); PG8_WAIT_L(0); PG8_BAR; PG8_MMA(1, 0, At, B0); PG8_MMA(1, 1, At, B1); PG8_BAR; PG8_SCHED;
	s_setprio 1
	s_waitcnt lgkmcnt(0)
	v_mfma_f32_16x16x32_bf16 v[2:5], v[144:147], v[176:179], v[2:5]
	v_mfma_f32_16x16x32_bf16 v[6:9], v[152:155], v[176:179], v[6:9]
	v_mfma_f32_16x16x32_bf16 v[22:25], v[144:147], v[184:187], v[22:25]
	v_mfma_f32_16x16x32_bf16 v[18:21], v[152:155], v[184:187], v[18:21]
	v_mfma_f32_16x16x32_bf16 v[38:41], v[144:147], v[192:195], v[38:41]
	v_mfma_f32_16x16x32_bf16 v[34:37], v[152:155], v[192:195], v[34:37]
	v_mfma_f32_16x16x32_bf16 v[54:57], v[144:147], v[200:203], v[54:57]
	v_mfma_f32_16x16x32_bf16 v[50:53], v[152:155], v[200:203], v[50:53]
	v_mfma_f32_16x16x32_bf16 v[2:5], v[148:151], v[180:183], v[2:5]
	v_mfma_f32_16x16x32_bf16 v[6:9], v[156:159], v[180:183], v[6:9]
	v_mfma_f32_16x16x32_bf16 v[22:25], v[148:151], v[188:191], v[22:25]
	v_mfma_f32_16x16x32_bf16 v[18:21], v[156:159], v[188:191], v[18:21]
	v_mfma_f32_16x16x32_bf16 v[38:41], v[148:151], v[196:199], v[38:41]
	v_mfma_f32_16x16x32_bf16 v[34:37], v[156:159], v[196:199], v[34:37]
	v_mfma_f32_16x16x32_bf16 v[54:57], v[148:151], v[204:207], v[54:57]
	v_mfma_f32_16x16x32_bf16 v[50:53], v[156:159], v[204:207], v[50:53]
	v_mfma_f32_16x16x32_bf16 v[10:13], v[160:163], v[176:179], v[10:13]
	v_mfma_f32_16x16x32_bf16 v[14:17], v[168:171], v[176:179], v[14:17]
	v_mfma_f32_16x16x32_bf16 v[26:29], v[160:163], v[184:187], v[26:29]
	v_mfma_f32_16x16x32_bf16 v[30:33], v[168:171], v[184:187], v[30:33]
	v_mfma_f32_16x16x32_bf16 v[42:45], v[160:163], v[192:195], v[42:45]
	v_mfma_f32_16x16x32_bf16 v[46:49], v[168:171], v[192:195], v[46:49]
	v_mfma_f32_16x16x32_bf16 v[58:61], v[160:163], v[200:203], v[58:61]
	v_mfma_f32_16x16x32_bf16 v[62:65], v[168:171], v[200:203], v[62:65]
	v_mfma_f32_16x16x32_bf16 v[10:13], v[164:167], v[180:183], v[10:13]
	v_mfma_f32_16x16x32_bf16 v[14:17], v[172:175], v[180:183], v[14:17]
	v_mfma_f32_16x16x32_bf16 v[26:29], v[164:167], v[188:191], v[26:29]
	v_mfma_f32_16x16x32_bf16 v[30:33], v[172:175], v[188:191], v[30:33]
	v_mfma_f32_16x16x32_bf16 v[42:45], v[164:167], v[196:199], v[42:45]
	v_mfma_f32_16x16x32_bf16 v[46:49], v[172:175], v[196:199], v[46:49]
	v_mfma_f32_16x16x32_bf16 v[58:61], v[164:167], v[204:207], v[58:61]
	v_mfma_f32_16x16x32_bf16 v[62:65], v[172:175], v[204:207], v[62:65]
	s_setprio 0
	s_barrier
	s_add_i32 s2, s2, s57
	v_lshl_add_u64 v[140:141], v[140:141], 0, s[26:27]
	s_mov_b32 m0, s2
	ds_read_b128 v[176:179], v139 offset:49152
	ds_read_b128 v[180:183], v139 offset:50176
	ds_read_b128 v[184:187], v139 offset:51200
	ds_read_b128 v[188:191], v139 offset:52224
	ds_read_b128 v[192:195], v139 offset:53248
	ds_read_b128 v[196:199], v139 offset:54272
	ds_read_b128 v[200:203], v139 offset:55296
	ds_read_b128 v[204:207], v139 offset:56320
	global_load_lds_dwordx4 v[140:141], off
	s_add_i32 m0, s2, 0x2000
	s_add_u32 s46, s46, 0x40080
	v_lshl_add_u64 v[140:141], v[208:209], 0, s[26:27]
	s_addc_u32 s47, s47, 0
	s_add_i32 s2, s81, s57
	global_load_lds_dwordx4 v[140:141], off
	v_lshl_add_u64 v[140:141], s[46:47], 0, v[130:131]
	s_mov_b32 m0, s2
	s_nop 0
	global_load_lds_dwordx4 v[140:141], off
	v_lshl_add_u64 v[140:141], s[46:47], 0, v[132:133]
	s_add_i32 m0, s2, 0x2000
	s_nop 0
	global_load_lds_dwordx4 v[140:141], off
	v_lshl_add_u64 v[140:141], v[210:211], 0, s[26:27]
	s_mov_b32 m0, s68
	s_nop 0
	global_load_lds_dwordx4 v[140:141], off
	v_lshl_add_u64 v[140:141], v[212:213], 0, s[26:27]
	s_mov_b32 m0, s69
	s_nop 0
	global_load_lds_dwordx4 v[140:141], off
	s_cmp_lt_i32 s80, 6
	s_cbranch_scc0 .Lxa_hi_pl
	s_cmp_lt_i32 s80, 2
	s_cbranch_scc0 .Lxa_23_pl
	s_cmp_lt_i32 s80, 0
	s_cbranch_scc0 .Lxa_1_pl
	v_add_f32_e32 v2, v2, v216
	v_add_f32_e32 v3, v3, v217
	v_add_f32_e32 v4, v4, v218
	v_add_f32_e32 v5, v5, v219
	v_add_f32_e32 v6, v6, v220
	v_add_f32_e32 v7, v7, v221
	v_add_f32_e32 v8, v8, v222
	v_add_f32_e32 v9, v9, v223
	v_add_f32_e32 v10, v10, v224
	v_add_f32_e32 v11, v11, v225
	v_add_f32_e32 v12, v12, v226
	v_add_f32_e32 v13, v13, v227
	v_add_f32_e32 v14, v14, v228
	v_add_f32_e32 v15, v15, v229
	v_add_f32_e32 v16, v16, v230
	v_add_f32_e32 v17, v17, v231
	s_branch .Lxa_done_pl
